# ffn_in phases fully hand-written: transposed accumulators, LDS-staged 16-byte HID stores
# speedup vs baseline: 1.0094x; 1.0094x over previous
.LBB0_951:
	s_cmp_gt_i32 s60, 8
	s_cselect_b64 s[2:3], -1, 0
	s_cmp_lt_i32 s61, 8
	s_cselect_b64 s[4:5], -1, 0
	s_or_b64 s[2:3], s[2:3], s[4:5]
	s_and_b64 vcc, exec, s[2:3]
	s_cbranch_vccnz .LBB0_1015
	s_load_dwordx2 s[4:5], s[0:1], 0xe0
	s_load_dword s16, s[0:1], 0xf0
	v_and_b32_e32 v240, 63, v162
	v_lshrrev_b32_e32 v247, 6, v162
	v_lshrrev_b32_e32 v242, 3, v240
	v_lshl_add_u32 v242, v247, 5, v242
	v_and_b32_e32 v243, 7, v240
	v_lshrrev_b32_e32 v244, 4, v240
	v_xor_b32_e32 v243, v243, v244
	v_lshlrev_b32_e32 v243, 4, v243
	v_mov_b32_e32 v241, 0x800
	v_mad_u32_u24 v248, v242, v241, v243
	v_xor_b32_e32 v249, 64, v248
	v_add_u32_e32 v249, 0x4000, v249
	v_add_u32_e32 v250, 0x8000, v248
	v_xor_b32_e32 v251, 64, v248
	v_add_u32_e32 v251, 0xc000, v251
	v_and_b32_e32 v241, 15, v240
	v_lshrrev_b32_e32 v242, 1, v241
	v_xor_b32_e32 v242, v242, v244
	v_lshlrev_b32_e32 v242, 4, v242
	v_lshl_or_b32 v242, v241, 7, v242
	v_lshrrev_b32_e32 v243, 1, v247
	v_lshl_or_b32 v252, v243, 13, v242
	v_xor_b32_e32 v253, 64, v252
	v_and_b32_e32 v243, 1, v247
	v_lshl_or_b32 v254, v243, 13, v242
	v_xor_b32_e32 v255, 64, v254
	v_and_b32_e32 v240, 63, v162
	v_and_b32_e32 v241, 15, v240
	v_lshrrev_b32_e32 v242, 4, v240
	v_mul_u32_u24_e32 v245, 0x1400, v247
	v_mul_u32_u24_e32 v243, 80, v241
	v_add_u32_e32 v243, v243, v245
	v_lshl_add_u32 v244, v242, 3, v243
	v_lshrrev_b32_e32 v243, 2, v240
	v_mul_u32_u24_e32 v246, 80, v243
	v_add_u32_e32 v246, v246, v245
	v_and_b32_e32 v241, 3, v240
	v_lshl_add_u32 v246, v241, 4, v246
	v_mov_b32_e32 v245, v244
	v_lshrrev_b32_e32 v242, 1, v247
	v_lshl_add_u32 v243, v242, 6, v243
	v_mov_b32_e32 v242, 0x1600
	v_mul_u32_u24_e32 v243, v243, v242
	v_and_b32_e32 v242, 1, v247
	v_lshl_add_u32 v243, v242, 6, v243
	v_lshl_add_u32 v239, v241, 4, v243
	s_waitcnt lgkmcnt(0)
	s_add_u32 s26, s4, 0x8b7a100
	s_addc_u32 s27, s5, 0
	s_add_u32 s28, s4, 0x2480000
	s_addc_u32 s29, s5, 0
	s_mov_b32 s15, s58
.Lf8_tile:
	s_cmp_lt_u32 s15, 0xb00
	s_cbranch_scc0 .Lf8_end
	s_and_b32 s2, s15, 63
	s_lshr_b32 s3, s15, 6
	s_lshl_b32 s14, s2, 18
	s_add_u32 s8, s26, s14
	s_addc_u32 s9, s27, 0
	s_lshl_b32 s14, s3, 18
	s_add_u32 s10, s28, s14
	s_addc_u32 s11, s29, 0
	s_mul_i32 s14, s2, 0xb0000
	s_lshl_b32 s6, s3, 7
	s_add_u32 s14, s14, s6
	s_add_u32 s20, s4, 0x9b7a100
	s_addc_u32 s21, s5, 0
	s_add_u32 s20, s20, s14
	s_addc_u32 s21, s21, 0
	v_readfirstlane_b32 s12, v247
	s_nop 3
	s_lshl_b32 s12, s12, 12
	s_add_u32 m0, s12, 0x0
	v_mov_b32_e32 v0, 0
	global_load_lds_dwordx4 v248, s[8:9]
	v_mov_b32_e32 v1, 0
	s_add_u32 m0, s12, 0x400
	v_mov_b32_e32 v2, 0
	global_load_lds_dwordx4 v249, s[8:9]
	v_mov_b32_e32 v3, 0
	s_add_u32 m0, s12, 0x800
	v_mov_b32_e32 v4, 0
	global_load_lds_dwordx4 v250, s[8:9]
	v_mov_b32_e32 v5, 0
	s_add_u32 m0, s12, 0xc00
	v_mov_b32_e32 v6, 0
	global_load_lds_dwordx4 v251, s[8:9]
	v_mov_b32_e32 v7, 0
	s_add_u32 m0, s12, 0x8000
	v_mov_b32_e32 v8, 0
	global_load_lds_dwordx4 v248, s[10:11]
	v_mov_b32_e32 v9, 0
	s_add_u32 m0, s12, 0x8400
	v_mov_b32_e32 v10, 0
	global_load_lds_dwordx4 v249, s[10:11]
	v_mov_b32_e32 v11, 0
	s_add_u32 m0, s12, 0x8800
	v_mov_b32_e32 v12, 0
	global_load_lds_dwordx4 v250, s[10:11]
	v_mov_b32_e32 v13, 0
	s_add_u32 m0, s12, 0x8c00
	v_mov_b32_e32 v14, 0
	global_load_lds_dwordx4 v251, s[10:11]
	v_mov_b32_e32 v15, 0
	s_add_u32 s8, s8, 0x80
	s_addc_u32 s9, s9, 0
	s_add_u32 s10, s10, 0x80
	s_addc_u32 s11, s11, 0
	s_add_u32 m0, s12, 0x4000
	v_mov_b32_e32 v16, 0
	global_load_lds_dwordx4 v248, s[8:9]
	v_mov_b32_e32 v17, 0
	s_add_u32 m0, s12, 0x4400
	v_mov_b32_e32 v18, 0
	global_load_lds_dwordx4 v249, s[8:9]
	v_mov_b32_e32 v19, 0
	s_add_u32 m0, s12, 0x4800
	v_mov_b32_e32 v20, 0
	global_load_lds_dwordx4 v250, s[8:9]
	v_mov_b32_e32 v21, 0
	s_add_u32 m0, s12, 0x4c00
	v_mov_b32_e32 v22, 0
	global_load_lds_dwordx4 v251, s[8:9]
	v_mov_b32_e32 v23, 0
	s_add_u32 m0, s12, 0xc000
	v_mov_b32_e32 v24, 0
	global_load_lds_dwordx4 v248, s[10:11]
	v_mov_b32_e32 v25, 0
	s_add_u32 m0, s12, 0xc400
	v_mov_b32_e32 v26, 0
	global_load_lds_dwordx4 v249, s[10:11]
	v_mov_b32_e32 v27, 0
	s_add_u32 m0, s12, 0xc800
	v_mov_b32_e32 v28, 0
	global_load_lds_dwordx4 v250, s[10:11]
	v_mov_b32_e32 v29, 0
	s_add_u32 m0, s12, 0xcc00
	v_mov_b32_e32 v30, 0
	global_load_lds_dwordx4 v251, s[10:11]
	v_mov_b32_e32 v31, 0
	s_add_u32 s8, s8, 0x80
	s_addc_u32 s9, s9, 0
	s_add_u32 s10, s10, 0x80
	s_addc_u32 s11, s11, 0
	v_mov_b32_e32 v32, 0
	v_mov_b32_e32 v33, 0
	v_mov_b32_e32 v34, 0
	v_mov_b32_e32 v35, 0
	v_mov_b32_e32 v36, 0
	v_mov_b32_e32 v37, 0
	v_mov_b32_e32 v38, 0
	v_mov_b32_e32 v39, 0
	v_mov_b32_e32 v40, 0
	v_mov_b32_e32 v41, 0
	v_mov_b32_e32 v42, 0
	v_mov_b32_e32 v43, 0
	v_mov_b32_e32 v44, 0
	v_mov_b32_e32 v45, 0
	v_mov_b32_e32 v46, 0
	v_mov_b32_e32 v47, 0
	v_mov_b32_e32 v48, 0
	v_mov_b32_e32 v49, 0
	v_mov_b32_e32 v50, 0
	v_mov_b32_e32 v51, 0
	v_mov_b32_e32 v52, 0
	v_mov_b32_e32 v53, 0
	v_mov_b32_e32 v54, 0
	v_mov_b32_e32 v55, 0
	v_mov_b32_e32 v56, 0
	v_mov_b32_e32 v57, 0
	v_mov_b32_e32 v58, 0
	v_mov_b32_e32 v59, 0
	v_mov_b32_e32 v60, 0
	v_mov_b32_e32 v61, 0
	v_mov_b32_e32 v62, 0
	v_mov_b32_e32 v63, 0
	s_waitcnt vmcnt(8)
	s_barrier
	ds_read_b128 v[64:67], v252 offset:0
	ds_read_b128 v[96:99], v254 offset:32768
	ds_read_b128 v[100:103], v254 offset:34816
	ds_read_b128 v[104:107], v254 offset:36864
	ds_read_b128 v[108:111], v254 offset:38912
	ds_read_b128 v[68:71], v252 offset:2048
	ds_read_b128 v[72:75], v252 offset:4096
	ds_read_b128 v[76:79], v252 offset:6144
	ds_read_b128 v[80:83], v253 offset:0
	ds_read_b128 v[112:115], v255 offset:32768
	ds_read_b128 v[116:119], v255 offset:34816
	ds_read_b128 v[120:123], v255 offset:36864
	ds_read_b128 v[124:127], v255 offset:38912
	s_waitcnt lgkmcnt(11)
	v_mfma_f32_16x16x32_bf16 v[0:3], v[96:99], v[64:67], v[0:3]
	s_waitcnt lgkmcnt(10)
	v_mfma_f32_16x16x32_bf16 v[4:7], v[100:103], v[64:67], v[4:7]
	s_waitcnt lgkmcnt(9)
	v_mfma_f32_16x16x32_bf16 v[8:11], v[104:107], v[64:67], v[8:11]
	s_waitcnt lgkmcnt(8)
	v_mfma_f32_16x16x32_bf16 v[12:15], v[108:111], v[64:67], v[12:15]
	ds_read_b128 v[84:87], v253 offset:2048
	ds_read_b128 v[88:91], v253 offset:4096
	ds_read_b128 v[92:95], v253 offset:6144
	s_waitcnt lgkmcnt(10)
	v_mfma_f32_16x16x32_bf16 v[16:19], v[96:99], v[68:71], v[16:19]
	v_mfma_f32_16x16x32_bf16 v[20:23], v[100:103], v[68:71], v[20:23]
	v_mfma_f32_16x16x32_bf16 v[24:27], v[104:107], v[68:71], v[24:27]
	v_mfma_f32_16x16x32_bf16 v[28:31], v[108:111], v[68:71], v[28:31]
	s_waitcnt lgkmcnt(0)
	s_barrier
	s_add_u32 m0, s12, 0x0
	v_mfma_f32_16x16x32_bf16 v[32:35], v[96:99], v[72:75], v[32:35]
	global_load_lds_dwordx4 v248, s[8:9]
	s_add_u32 m0, s12, 0x400
	v_mfma_f32_16x16x32_bf16 v[36:39], v[100:103], v[72:75], v[36:39]
	global_load_lds_dwordx4 v249, s[8:9]
	s_add_u32 m0, s12, 0x800
	v_mfma_f32_16x16x32_bf16 v[40:43], v[104:107], v[72:75], v[40:43]
	global_load_lds_dwordx4 v250, s[8:9]
	s_add_u32 m0, s12, 0xc00
	v_mfma_f32_16x16x32_bf16 v[44:47], v[108:111], v[72:75], v[44:47]
	global_load_lds_dwordx4 v251, s[8:9]
	s_add_u32 m0, s12, 0x8000
	v_mfma_f32_16x16x32_bf16 v[48:51], v[96:99], v[76:79], v[48:51]
	global_load_lds_dwordx4 v248, s[10:11]
	s_add_u32 m0, s12, 0x8400
	v_mfma_f32_16x16x32_bf16 v[52:55], v[100:103], v[76:79], v[52:55]
	global_load_lds_dwordx4 v249, s[10:11]
	s_add_u32 m0, s12, 0x8800
	v_mfma_f32_16x16x32_bf16 v[56:59], v[104:107], v[76:79], v[56:59]
	global_load_lds_dwordx4 v250, s[10:11]
	s_add_u32 m0, s12, 0x8c00
	v_mfma_f32_16x16x32_bf16 v[60:63], v[108:111], v[76:79], v[60:63]
	global_load_lds_dwordx4 v251, s[10:11]
	s_add_u32 s8, s8, 0x80
	s_addc_u32 s9, s9, 0
	s_add_u32 s10, s10, 0x80
	s_addc_u32 s11, s11, 0
	s_waitcnt vmcnt(8)
	s_barrier
	ds_read_b128 v[64:67], v252 offset:16384
	ds_read_b128 v[96:99], v254 offset:49152
	ds_read_b128 v[100:103], v254 offset:51200
	ds_read_b128 v[104:107], v254 offset:53248
	ds_read_b128 v[108:111], v254 offset:55296
	ds_read_b128 v[68:71], v252 offset:18432
	ds_read_b128 v[72:75], v252 offset:20480
	ds_read_b128 v[76:79], v252 offset:22528
	v_mfma_f32_16x16x32_bf16 v[0:3], v[112:115], v[80:83], v[0:3]
	v_mfma_f32_16x16x32_bf16 v[4:7], v[116:119], v[80:83], v[4:7]
	v_mfma_f32_16x16x32_bf16 v[8:11], v[120:123], v[80:83], v[8:11]
	v_mfma_f32_16x16x32_bf16 v[12:15], v[124:127], v[80:83], v[12:15]
	v_mfma_f32_16x16x32_bf16 v[16:19], v[112:115], v[84:87], v[16:19]
	v_mfma_f32_16x16x32_bf16 v[20:23], v[116:119], v[84:87], v[20:23]
	v_mfma_f32_16x16x32_bf16 v[24:27], v[120:123], v[84:87], v[24:27]
	v_mfma_f32_16x16x32_bf16 v[28:31], v[124:127], v[84:87], v[28:31]
	v_mfma_f32_16x16x32_bf16 v[32:35], v[112:115], v[88:91], v[32:35]
	v_mfma_f32_16x16x32_bf16 v[36:39], v[116:119], v[88:91], v[36:39]
	v_mfma_f32_16x16x32_bf16 v[40:43], v[120:123], v[88:91], v[40:43]
	v_mfma_f32_16x16x32_bf16 v[44:47], v[124:127], v[88:91], v[44:47]
	v_mfma_f32_16x16x32_bf16 v[48:51], v[112:115], v[92:95], v[48:51]
	v_mfma_f32_16x16x32_bf16 v[52:55], v[116:119], v[92:95], v[52:55]
	v_mfma_f32_16x16x32_bf16 v[56:59], v[120:123], v[92:95], v[56:59]
	v_mfma_f32_16x16x32_bf16 v[60:63], v[124:127], v[92:95], v[60:63]
	ds_read_b128 v[80:83], v253 offset:16384
	ds_read_b128 v[112:115], v255 offset:49152
	ds_read_b128 v[116:119], v255 offset:51200
	ds_read_b128 v[120:123], v255 offset:53248
	ds_read_b128 v[124:127], v255 offset:55296
	ds_read_b128 v[84:87], v253 offset:18432
	ds_read_b128 v[88:91], v253 offset:20480
	ds_read_b128 v[92:95], v253 offset:22528
	s_waitcnt lgkmcnt(14)
	v_mfma_f32_16x16x32_bf16 v[0:3], v[96:99], v[64:67], v[0:3]
	s_waitcnt lgkmcnt(13)
	v_mfma_f32_16x16x32_bf16 v[4:7], v[100:103], v[64:67], v[4:7]
	s_waitcnt lgkmcnt(12)
	v_mfma_f32_16x16x32_bf16 v[8:11], v[104:107], v[64:67], v[8:11]
	s_waitcnt lgkmcnt(11)
	v_mfma_f32_16x16x32_bf16 v[12:15], v[108:111], v[64:67], v[12:15]
	s_waitcnt lgkmcnt(10)
	v_mfma_f32_16x16x32_bf16 v[16:19], v[96:99], v[68:71], v[16:19]
	v_mfma_f32_16x16x32_bf16 v[20:23], v[100:103], v[68:71], v[20:23]
	v_mfma_f32_16x16x32_bf16 v[24:27], v[104:107], v[68:71], v[24:27]
	v_mfma_f32_16x16x32_bf16 v[28:31], v[108:111], v[68:71], v[28:31]
	s_waitcnt lgkmcnt(0)
	s_barrier
	s_add_u32 m0, s12, 0x4000
	v_mfma_f32_16x16x32_bf16 v[32:35], v[96:99], v[72:75], v[32:35]
	global_load_lds_dwordx4 v248, s[8:9]
	s_add_u32 m0, s12, 0x4400
	v_mfma_f32_16x16x32_bf16 v[36:39], v[100:103], v[72:75], v[36:39]
	global_load_lds_dwordx4 v249, s[8:9]
	s_add_u32 m0, s12, 0x4800
	v_mfma_f32_16x16x32_bf16 v[40:43], v[104:107], v[72:75], v[40:43]
	global_load_lds_dwordx4 v250, s[8:9]
	s_add_u32 m0, s12, 0x4c00
	v_mfma_f32_16x16x32_bf16 v[44:47], v[108:111], v[72:75], v[44:47]
	global_load_lds_dwordx4 v251, s[8:9]
	s_add_u32 m0, s12, 0xc000
	v_mfma_f32_16x16x32_bf16 v[48:51], v[96:99], v[76:79], v[48:51]
	global_load_lds_dwordx4 v248, s[10:11]
	s_add_u32 m0, s12, 0xc400
	v_mfma_f32_16x16x32_bf16 v[52:55], v[100:103], v[76:79], v[52:55]
	global_load_lds_dwordx4 v249, s[10:11]
	s_add_u32 m0, s12, 0xc800
	v_mfma_f32_16x16x32_bf16 v[56:59], v[104:107], v[76:79], v[56:59]
	global_load_lds_dwordx4 v250, s[10:11]
	s_add_u32 m0, s12, 0xcc00
	v_mfma_f32_16x16x32_bf16 v[60:63], v[108:111], v[76:79], v[60:63]
	global_load_lds_dwordx4 v251, s[10:11]
	s_add_u32 s8, s8, 0x80
	s_addc_u32 s9, s9, 0
	s_add_u32 s10, s10, 0x80
	s_addc_u32 s11, s11, 0
	s_mov_b32 s13, 6
.Lf8_loop:
	s_waitcnt vmcnt(8)
	s_barrier
	ds_read_b128 v[64:67], v252 offset:0
	ds_read_b128 v[96:99], v254 offset:32768
	ds_read_b128 v[100:103], v254 offset:34816
	ds_read_b128 v[104:107], v254 offset:36864
	ds_read_b128 v[108:111], v254 offset:38912
	ds_read_b128 v[68:71], v252 offset:2048
	ds_read_b128 v[72:75], v252 offset:4096
	ds_read_b128 v[76:79], v252 offset:6144
	v_mfma_f32_16x16x32_bf16 v[0:3], v[112:115], v[80:83], v[0:3]
	v_mfma_f32_16x16x32_bf16 v[4:7], v[116:119], v[80:83], v[4:7]
	v_mfma_f32_16x16x32_bf16 v[8:11], v[120:123], v[80:83], v[8:11]
	v_mfma_f32_16x16x32_bf16 v[12:15], v[124:127], v[80:83], v[12:15]
	v_mfma_f32_16x16x32_bf16 v[16:19], v[112:115], v[84:87], v[16:19]
	v_mfma_f32_16x16x32_bf16 v[20:23], v[116:119], v[84:87], v[20:23]
	v_mfma_f32_16x16x32_bf16 v[24:27], v[120:123], v[84:87], v[24:27]
	v_mfma_f32_16x16x32_bf16 v[28:31], v[124:127], v[84:87], v[28:31]
	v_mfma_f32_16x16x32_bf16 v[32:35], v[112:115], v[88:91], v[32:35]
	v_mfma_f32_16x16x32_bf16 v[36:39], v[116:119], v[88:91], v[36:39]
	v_mfma_f32_16x16x32_bf16 v[40:43], v[120:123], v[88:91], v[40:43]
	v_mfma_f32_16x16x32_bf16 v[44:47], v[124:127], v[88:91], v[44:47]
	v_mfma_f32_16x16x32_bf16 v[48:51], v[112:115], v[92:95], v[48:51]
	v_mfma_f32_16x16x32_bf16 v[52:55], v[116:119], v[92:95], v[52:55]
	v_mfma_f32_16x16x32_bf16 v[56:59], v[120:123], v[92:95], v[56:59]
	v_mfma_f32_16x16x32_bf16 v[60:63], v[124:127], v[92:95], v[60:63]
	ds_read_b128 v[80:83], v253 offset:0
	ds_read_b128 v[112:115], v255 offset:32768
	ds_read_b128 v[116:119], v255 offset:34816
	ds_read_b128 v[120:123], v255 offset:36864
	ds_read_b128 v[124:127], v255 offset:38912
	ds_read_b128 v[84:87], v253 offset:2048
	ds_read_b128 v[88:91], v253 offset:4096
	ds_read_b128 v[92:95], v253 offset:6144
	s_waitcnt lgkmcnt(14)
	v_mfma_f32_16x16x32_bf16 v[0:3], v[96:99], v[64:67], v[0:3]
	s_waitcnt lgkmcnt(13)
	v_mfma_f32_16x16x32_bf16 v[4:7], v[100:103], v[64:67], v[4:7]
	s_waitcnt lgkmcnt(12)
	v_mfma_f32_16x16x32_bf16 v[8:11], v[104:107], v[64:67], v[8:11]
	s_waitcnt lgkmcnt(11)
	v_mfma_f32_16x16x32_bf16 v[12:15], v[108:111], v[64:67], v[12:15]
	s_waitcnt lgkmcnt(10)
	v_mfma_f32_16x16x32_bf16 v[16:19], v[96:99], v[68:71], v[16:19]
	v_mfma_f32_16x16x32_bf16 v[20:23], v[100:103], v[68:71], v[20:23]
	v_mfma_f32_16x16x32_bf16 v[24:27], v[104:107], v[68:71], v[24:27]
	v_mfma_f32_16x16x32_bf16 v[28:31], v[108:111], v[68:71], v[28:31]
	s_waitcnt lgkmcnt(0)
	s_barrier
	s_add_u32 m0, s12, 0x0
	v_mfma_f32_16x16x32_bf16 v[32:35], v[96:99], v[72:75], v[32:35]
	global_load_lds_dwordx4 v248, s[8:9]
	s_add_u32 m0, s12, 0x400
	v_mfma_f32_16x16x32_bf16 v[36:39], v[100:103], v[72:75], v[36:39]
	global_load_lds_dwordx4 v249, s[8:9]
	s_add_u32 m0, s12, 0x800
	v_mfma_f32_16x16x32_bf16 v[40:43], v[104:107], v[72:75], v[40:43]
	global_load_lds_dwordx4 v250, s[8:9]
	s_add_u32 m0, s12, 0xc00
	v_mfma_f32_16x16x32_bf16 v[44:47], v[108:111], v[72:75], v[44:47]
	global_load_lds_dwordx4 v251, s[8:9]
	s_add_u32 m0, s12, 0x8000
	v_mfma_f32_16x16x32_bf16 v[48:51], v[96:99], v[76:79], v[48:51]
	global_load_lds_dwordx4 v248, s[10:11]
	s_add_u32 m0, s12, 0x8400
	v_mfma_f32_16x16x32_bf16 v[52:55], v[100:103], v[76:79], v[52:55]
	global_load_lds_dwordx4 v249, s[10:11]
	s_add_u32 m0, s12, 0x8800
	v_mfma_f32_16x16x32_bf16 v[56:59], v[104:107], v[76:79], v[56:59]
	global_load_lds_dwordx4 v250, s[10:11]
	s_add_u32 m0, s12, 0x8c00
	v_mfma_f32_16x16x32_bf16 v[60:63], v[108:111], v[76:79], v[60:63]
	global_load_lds_dwordx4 v251, s[10:11]
	s_add_u32 s8, s8, 0x80
	s_addc_u32 s9, s9, 0
	s_add_u32 s10, s10, 0x80
	s_addc_u32 s11, s11, 0
	s_waitcnt vmcnt(8)
	s_barrier
	ds_read_b128 v[64:67], v252 offset:16384
	ds_read_b128 v[96:99], v254 offset:49152
	ds_read_b128 v[100:103], v254 offset:51200
	ds_read_b128 v[104:107], v254 offset:53248
	ds_read_b128 v[108:111], v254 offset:55296
	ds_read_b128 v[68:71], v252 offset:18432
	ds_read_b128 v[72:75], v252 offset:20480
	ds_read_b128 v[76:79], v252 offset:22528
	v_mfma_f32_16x16x32_bf16 v[0:3], v[112:115], v[80:83], v[0:3]
	v_mfma_f32_16x16x32_bf16 v[4:7], v[116:119], v[80:83], v[4:7]
	v_mfma_f32_16x16x32_bf16 v[8:11], v[120:123], v[80:83], v[8:11]
	v_mfma_f32_16x16x32_bf16 v[12:15], v[124:127], v[80:83], v[12:15]
	v_mfma_f32_16x16x32_bf16 v[16:19], v[112:115], v[84:87], v[16:19]
	v_mfma_f32_16x16x32_bf16 v[20:23], v[116:119], v[84:87], v[20:23]
	v_mfma_f32_16x16x32_bf16 v[24:27], v[120:123], v[84:87], v[24:27]
	v_mfma_f32_16x16x32_bf16 v[28:31], v[124:127], v[84:87], v[28:31]
	v_mfma_f32_16x16x32_bf16 v[32:35], v[112:115], v[88:91], v[32:35]
	v_mfma_f32_16x16x32_bf16 v[36:39], v[116:119], v[88:91], v[36:39]
	v_mfma_f32_16x16x32_bf16 v[40:43], v[120:123], v[88:91], v[40:43]
	v_mfma_f32_16x16x32_bf16 v[44:47], v[124:127], v[88:91], v[44:47]
	v_mfma_f32_16x16x32_bf16 v[48:51], v[112:115], v[92:95], v[48:51]
	v_mfma_f32_16x16x32_bf16 v[52:55], v[116:119], v[92:95], v[52:55]
	v_mfma_f32_16x16x32_bf16 v[56:59], v[120:123], v[92:95], v[56:59]
	v_mfma_f32_16x16x32_bf16 v[60:63], v[124:127], v[92:95], v[60:63]
	ds_read_b128 v[80:83], v253 offset:16384
	ds_read_b128 v[112:115], v255 offset:49152
	ds_read_b128 v[116:119], v255 offset:51200
	ds_read_b128 v[120:123], v255 offset:53248
	ds_read_b128 v[124:127], v255 offset:55296
	ds_read_b128 v[84:87], v253 offset:18432
	ds_read_b128 v[88:91], v253 offset:20480
	ds_read_b128 v[92:95], v253 offset:22528
	s_waitcnt lgkmcnt(14)
	v_mfma_f32_16x16x32_bf16 v[0:3], v[96:99], v[64:67], v[0:3]
	s_waitcnt lgkmcnt(13)
	v_mfma_f32_16x16x32_bf16 v[4:7], v[100:103], v[64:67], v[4:7]
	s_waitcnt lgkmcnt(12)
	v_mfma_f32_16x16x32_bf16 v[8:11], v[104:107], v[64:67], v[8:11]
	s_waitcnt lgkmcnt(11)
	v_mfma_f32_16x16x32_bf16 v[12:15], v[108:111], v[64:67], v[12:15]
	s_waitcnt lgkmcnt(10)
	v_mfma_f32_16x16x32_bf16 v[16:19], v[96:99], v[68:71], v[16:19]
	v_mfma_f32_16x16x32_bf16 v[20:23], v[100:103], v[68:71], v[20:23]
	v_mfma_f32_16x16x32_bf16 v[24:27], v[104:107], v[68:71], v[24:27]
	v_mfma_f32_16x16x32_bf16 v[28:31], v[108:111], v[68:71], v[28:31]
	s_waitcnt lgkmcnt(0)
	s_barrier
	s_add_u32 m0, s12, 0x4000
	v_mfma_f32_16x16x32_bf16 v[32:35], v[96:99], v[72:75], v[32:35]
	global_load_lds_dwordx4 v248, s[8:9]
	s_add_u32 m0, s12, 0x4400
	v_mfma_f32_16x16x32_bf16 v[36:39], v[100:103], v[72:75], v[36:39]
	global_load_lds_dwordx4 v249, s[8:9]
	s_add_u32 m0, s12, 0x4800
	v_mfma_f32_16x16x32_bf16 v[40:43], v[104:107], v[72:75], v[40:43]
	global_load_lds_dwordx4 v250, s[8:9]
	s_add_u32 m0, s12, 0x4c00
	v_mfma_f32_16x16x32_bf16 v[44:47], v[108:111], v[72:75], v[44:47]
	global_load_lds_dwordx4 v251, s[8:9]
	s_add_u32 m0, s12, 0xc000
	v_mfma_f32_16x16x32_bf16 v[48:51], v[96:99], v[76:79], v[48:51]
	global_load_lds_dwordx4 v248, s[10:11]
	s_add_u32 m0, s12, 0xc400
	v_mfma_f32_16x16x32_bf16 v[52:55], v[100:103], v[76:79], v[52:55]
	global_load_lds_dwordx4 v249, s[10:11]
	s_add_u32 m0, s12, 0xc800
	v_mfma_f32_16x16x32_bf16 v[56:59], v[104:107], v[76:79], v[56:59]
	global_load_lds_dwordx4 v250, s[10:11]
	s_add_u32 m0, s12, 0xcc00
	v_mfma_f32_16x16x32_bf16 v[60:63], v[108:111], v[76:79], v[60:63]
	global_load_lds_dwordx4 v251, s[10:11]
	s_add_u32 s8, s8, 0x80
	s_addc_u32 s9, s9, 0
	s_add_u32 s10, s10, 0x80
	s_addc_u32 s11, s11, 0
	s_sub_u32 s13, s13, 1
	s_cmp_lg_u32 s13, 0
	s_cbranch_scc1 .Lf8_loop
	s_waitcnt vmcnt(8)
	s_barrier
	ds_read_b128 v[64:67], v252 offset:0
	ds_read_b128 v[96:99], v254 offset:32768
	ds_read_b128 v[100:103], v254 offset:34816
	ds_read_b128 v[104:107], v254 offset:36864
	ds_read_b128 v[108:111], v254 offset:38912
	ds_read_b128 v[68:71], v252 offset:2048
	ds_read_b128 v[72:75], v252 offset:4096
	ds_read_b128 v[76:79], v252 offset:6144
	v_mfma_f32_16x16x32_bf16 v[0:3], v[112:115], v[80:83], v[0:3]
	v_mfma_f32_16x16x32_bf16 v[4:7], v[116:119], v[80:83], v[4:7]
	v_mfma_f32_16x16x32_bf16 v[8:11], v[120:123], v[80:83], v[8:11]
	v_mfma_f32_16x16x32_bf16 v[12:15], v[124:127], v[80:83], v[12:15]
	v_mfma_f32_16x16x32_bf16 v[16:19], v[112:115], v[84:87], v[16:19]
	v_mfma_f32_16x16x32_bf16 v[20:23], v[116:119], v[84:87], v[20:23]
	v_mfma_f32_16x16x32_bf16 v[24:27], v[120:123], v[84:87], v[24:27]
	v_mfma_f32_16x16x32_bf16 v[28:31], v[124:127], v[84:87], v[28:31]
	v_mfma_f32_16x16x32_bf16 v[32:35], v[112:115], v[88:91], v[32:35]
	v_mfma_f32_16x16x32_bf16 v[36:39], v[116:119], v[88:91], v[36:39]
	v_mfma_f32_16x16x32_bf16 v[40:43], v[120:123], v[88:91], v[40:43]
	v_mfma_f32_16x16x32_bf16 v[44:47], v[124:127], v[88:91], v[44:47]
	v_mfma_f32_16x16x32_bf16 v[48:51], v[112:115], v[92:95], v[48:51]
	v_mfma_f32_16x16x32_bf16 v[52:55], v[116:119], v[92:95], v[52:55]
	v_mfma_f32_16x16x32_bf16 v[56:59], v[120:123], v[92:95], v[56:59]
	v_mfma_f32_16x16x32_bf16 v[60:63], v[124:127], v[92:95], v[60:63]
	ds_read_b128 v[80:83], v253 offset:0
	ds_read_b128 v[112:115], v255 offset:32768
	ds_read_b128 v[116:119], v255 offset:34816
	ds_read_b128 v[120:123], v255 offset:36864
	ds_read_b128 v[124:127], v255 offset:38912
	ds_read_b128 v[84:87], v253 offset:2048
	ds_read_b128 v[88:91], v253 offset:4096
	ds_read_b128 v[92:95], v253 offset:6144
	s_waitcnt lgkmcnt(14)
	v_mfma_f32_16x16x32_bf16 v[0:3], v[96:99], v[64:67], v[0:3]
	s_waitcnt lgkmcnt(13)
	v_mfma_f32_16x16x32_bf16 v[4:7], v[100:103], v[64:67], v[4:7]
	s_waitcnt lgkmcnt(12)
	v_mfma_f32_16x16x32_bf16 v[8:11], v[104:107], v[64:67], v[8:11]
	s_waitcnt lgkmcnt(11)
	v_mfma_f32_16x16x32_bf16 v[12:15], v[108:111], v[64:67], v[12:15]
	s_waitcnt lgkmcnt(10)
	v_mfma_f32_16x16x32_bf16 v[16:19], v[96:99], v[68:71], v[16:19]
	v_mfma_f32_16x16x32_bf16 v[20:23], v[100:103], v[68:71], v[20:23]
	v_mfma_f32_16x16x32_bf16 v[24:27], v[104:107], v[68:71], v[24:27]
	v_mfma_f32_16x16x32_bf16 v[28:31], v[108:111], v[68:71], v[28:31]
	s_waitcnt lgkmcnt(0)
	s_barrier
	v_mfma_f32_16x16x32_bf16 v[32:35], v[96:99], v[72:75], v[32:35]
	v_mfma_f32_16x16x32_bf16 v[36:39], v[100:103], v[72:75], v[36:39]
	v_mfma_f32_16x16x32_bf16 v[40:43], v[104:107], v[72:75], v[40:43]
	v_mfma_f32_16x16x32_bf16 v[44:47], v[108:111], v[72:75], v[44:47]
	v_mfma_f32_16x16x32_bf16 v[48:51], v[96:99], v[76:79], v[48:51]
	v_mfma_f32_16x16x32_bf16 v[52:55], v[100:103], v[76:79], v[52:55]
	v_mfma_f32_16x16x32_bf16 v[56:59], v[104:107], v[76:79], v[56:59]
	v_mfma_f32_16x16x32_bf16 v[60:63], v[108:111], v[76:79], v[60:63]
	s_waitcnt vmcnt(0)
	s_barrier
	ds_read_b128 v[64:67], v252 offset:16384
	ds_read_b128 v[96:99], v254 offset:49152
	ds_read_b128 v[100:103], v254 offset:51200
	ds_read_b128 v[104:107], v254 offset:53248
	ds_read_b128 v[108:111], v254 offset:55296
	ds_read_b128 v[68:71], v252 offset:18432
	ds_read_b128 v[72:75], v252 offset:20480
	ds_read_b128 v[76:79], v252 offset:22528
	v_mfma_f32_16x16x32_bf16 v[0:3], v[112:115], v[80:83], v[0:3]
	v_mfma_f32_16x16x32_bf16 v[4:7], v[116:119], v[80:83], v[4:7]
	v_mfma_f32_16x16x32_bf16 v[8:11], v[120:123], v[80:83], v[8:11]
	v_mfma_f32_16x16x32_bf16 v[12:15], v[124:127], v[80:83], v[12:15]
	v_mfma_f32_16x16x32_bf16 v[16:19], v[112:115], v[84:87], v[16:19]
	v_mfma_f32_16x16x32_bf16 v[20:23], v[116:119], v[84:87], v[20:23]
	v_mfma_f32_16x16x32_bf16 v[24:27], v[120:123], v[84:87], v[24:27]
	v_mfma_f32_16x16x32_bf16 v[28:31], v[124:127], v[84:87], v[28:31]
	v_mfma_f32_16x16x32_bf16 v[32:35], v[112:115], v[88:91], v[32:35]
	v_mfma_f32_16x16x32_bf16 v[36:39], v[116:119], v[88:91], v[36:39]
	v_mfma_f32_16x16x32_bf16 v[40:43], v[120:123], v[88:91], v[40:43]
	v_mfma_f32_16x16x32_bf16 v[44:47], v[124:127], v[88:91], v[44:47]
	v_mfma_f32_16x16x32_bf16 v[48:51], v[112:115], v[92:95], v[48:51]
	v_mfma_f32_16x16x32_bf16 v[52:55], v[116:119], v[92:95], v[52:55]
	v_mfma_f32_16x16x32_bf16 v[56:59], v[120:123], v[92:95], v[56:59]
	v_mfma_f32_16x16x32_bf16 v[60:63], v[124:127], v[92:95], v[60:63]
	ds_read_b128 v[80:83], v253 offset:16384
	ds_read_b128 v[112:115], v255 offset:49152
	ds_read_b128 v[116:119], v255 offset:51200
	ds_read_b128 v[120:123], v255 offset:53248
	ds_read_b128 v[124:127], v255 offset:55296
	ds_read_b128 v[84:87], v253 offset:18432
	ds_read_b128 v[88:91], v253 offset:20480
	ds_read_b128 v[92:95], v253 offset:22528
	s_waitcnt lgkmcnt(14)
	v_mfma_f32_16x16x32_bf16 v[0:3], v[96:99], v[64:67], v[0:3]
	s_waitcnt lgkmcnt(13)
	v_mfma_f32_16x16x32_bf16 v[4:7], v[100:103], v[64:67], v[4:7]
	s_waitcnt lgkmcnt(12)
	v_mfma_f32_16x16x32_bf16 v[8:11], v[104:107], v[64:67], v[8:11]
	s_waitcnt lgkmcnt(11)
	v_mfma_f32_16x16x32_bf16 v[12:15], v[108:111], v[64:67], v[12:15]
	s_waitcnt lgkmcnt(10)
	v_mfma_f32_16x16x32_bf16 v[16:19], v[96:99], v[68:71], v[16:19]
	v_mfma_f32_16x16x32_bf16 v[20:23], v[100:103], v[68:71], v[20:23]
	v_mfma_f32_16x16x32_bf16 v[24:27], v[104:107], v[68:71], v[24:27]
	v_mfma_f32_16x16x32_bf16 v[28:31], v[108:111], v[68:71], v[28:31]
	s_waitcnt lgkmcnt(0)
	s_barrier
	v_mfma_f32_16x16x32_bf16 v[32:35], v[96:99], v[72:75], v[32:35]
	v_mfma_f32_16x16x32_bf16 v[36:39], v[100:103], v[72:75], v[36:39]
	v_mfma_f32_16x16x32_bf16 v[40:43], v[104:107], v[72:75], v[40:43]
	v_mfma_f32_16x16x32_bf16 v[44:47], v[108:111], v[72:75], v[44:47]
	v_mfma_f32_16x16x32_bf16 v[48:51], v[96:99], v[76:79], v[48:51]
	v_mfma_f32_16x16x32_bf16 v[52:55], v[100:103], v[76:79], v[52:55]
	v_mfma_f32_16x16x32_bf16 v[56:59], v[104:107], v[76:79], v[56:59]
	v_mfma_f32_16x16x32_bf16 v[60:63], v[108:111], v[76:79], v[60:63]
	v_mfma_f32_16x16x32_bf16 v[0:3], v[112:115], v[80:83], v[0:3]
	v_mfma_f32_16x16x32_bf16 v[4:7], v[116:119], v[80:83], v[4:7]
	v_mfma_f32_16x16x32_bf16 v[8:11], v[120:123], v[80:83], v[8:11]
	v_mfma_f32_16x16x32_bf16 v[12:15], v[124:127], v[80:83], v[12:15]
	v_mfma_f32_16x16x32_bf16 v[16:19], v[112:115], v[84:87], v[16:19]
	v_mfma_f32_16x16x32_bf16 v[20:23], v[116:119], v[84:87], v[20:23]
	v_mfma_f32_16x16x32_bf16 v[24:27], v[120:123], v[84:87], v[24:27]
	v_mfma_f32_16x16x32_bf16 v[28:31], v[124:127], v[84:87], v[28:31]
	v_mfma_f32_16x16x32_bf16 v[32:35], v[112:115], v[88:91], v[32:35]
	v_mfma_f32_16x16x32_bf16 v[36:39], v[116:119], v[88:91], v[36:39]
	v_mfma_f32_16x16x32_bf16 v[40:43], v[120:123], v[88:91], v[40:43]
	v_mfma_f32_16x16x32_bf16 v[44:47], v[124:127], v[88:91], v[44:47]
	v_mfma_f32_16x16x32_bf16 v[48:51], v[112:115], v[92:95], v[48:51]
	v_mfma_f32_16x16x32_bf16 v[52:55], v[116:119], v[92:95], v[52:55]
	v_mfma_f32_16x16x32_bf16 v[56:59], v[120:123], v[92:95], v[56:59]
	v_mfma_f32_16x16x32_bf16 v[60:63], v[124:127], v[92:95], v[60:63]
	s_nop 7
	s_nop 1
	v_mul_f32_e32 v130, 0xbfb8aa3b, v0
	v_mul_f32_e32 v131, 0xbfb8aa3b, v1
	v_mul_f32_e32 v132, 0xbfb8aa3b, v2
	v_mul_f32_e32 v133, 0xbfb8aa3b, v3
	v_mul_f32_e32 v134, 0xbfb8aa3b, v4
	v_mul_f32_e32 v135, 0xbfb8aa3b, v5
	v_mul_f32_e32 v136, 0xbfb8aa3b, v6
	v_mul_f32_e32 v137, 0xbfb8aa3b, v7
	v_exp_f32_e32 v130, v130
	v_exp_f32_e32 v131, v131
	v_exp_f32_e32 v132, v132
	v_exp_f32_e32 v133, v133
	v_exp_f32_e32 v134, v134
	v_exp_f32_e32 v135, v135
	v_exp_f32_e32 v136, v136
	v_exp_f32_e32 v137, v137
	v_add_f32_e32 v130, 1.0, v130
	v_add_f32_e32 v131, 1.0, v131
	v_add_f32_e32 v132, 1.0, v132
	v_add_f32_e32 v133, 1.0, v133
	v_add_f32_e32 v134, 1.0, v134
	v_add_f32_e32 v135, 1.0, v135
	v_add_f32_e32 v136, 1.0, v136
	v_add_f32_e32 v137, 1.0, v137
	v_rcp_f32_e32 v130, v130
	v_rcp_f32_e32 v131, v131
	v_rcp_f32_e32 v132, v132
	v_rcp_f32_e32 v133, v133
	v_rcp_f32_e32 v134, v134
	v_rcp_f32_e32 v135, v135
	v_rcp_f32_e32 v136, v136
	v_rcp_f32_e32 v137, v137
	v_mul_f32_e32 v130, v0, v130
	v_mul_f32_e32 v131, v1, v131
	v_mul_f32_e32 v132, v2, v132
	v_mul_f32_e32 v133, v3, v133
	v_mul_f32_e32 v134, v4, v134
	v_mul_f32_e32 v135, v5, v135
	v_mul_f32_e32 v136, v6, v136
	v_mul_f32_e32 v137, v7, v137
	v_mul_f32_e32 v130, v8, v130
	v_mul_f32_e32 v131, v9, v131
	v_mul_f32_e32 v132, v10, v132
	v_mul_f32_e32 v133, v11, v133
	v_mul_f32_e32 v134, v12, v134
	v_mul_f32_e32 v135, v13, v135
	v_mul_f32_e32 v136, v14, v136
	v_mul_f32_e32 v137, v15, v137
	v_cvt_pk_bf16_f32 v0, v130, v131
	v_cvt_pk_bf16_f32 v1, v132, v133
	v_cvt_pk_bf16_f32 v2, v134, v135
	v_cvt_pk_bf16_f32 v3, v136, v137
	ds_write_b64 v245, v[0:1] offset:0
	ds_write_b64 v245, v[2:3] offset:32
	v_mul_f32_e32 v130, 0xbfb8aa3b, v16
	v_mul_f32_e32 v131, 0xbfb8aa3b, v17
	v_mul_f32_e32 v132, 0xbfb8aa3b, v18
	v_mul_f32_e32 v133, 0xbfb8aa3b, v19
	v_mul_f32_e32 v134, 0xbfb8aa3b, v20
	v_mul_f32_e32 v135, 0xbfb8aa3b, v21
	v_mul_f32_e32 v136, 0xbfb8aa3b, v22
	v_mul_f32_e32 v137, 0xbfb8aa3b, v23
	v_exp_f32_e32 v130, v130
	v_exp_f32_e32 v131, v131
	v_exp_f32_e32 v132, v132
	v_exp_f32_e32 v133, v133
	v_exp_f32_e32 v134, v134
	v_exp_f32_e32 v135, v135
	v_exp_f32_e32 v136, v136
	v_exp_f32_e32 v137, v137
	v_add_f32_e32 v130, 1.0, v130
	v_add_f32_e32 v131, 1.0, v131
	v_add_f32_e32 v132, 1.0, v132
	v_add_f32_e32 v133, 1.0, v133
	v_add_f32_e32 v134, 1.0, v134
	v_add_f32_e32 v135, 1.0, v135
	v_add_f32_e32 v136, 1.0, v136
	v_add_f32_e32 v137, 1.0, v137
	v_rcp_f32_e32 v130, v130
	v_rcp_f32_e32 v131, v131
	v_rcp_f32_e32 v132, v132
	v_rcp_f32_e32 v133, v133
	v_rcp_f32_e32 v134, v134
	v_rcp_f32_e32 v135, v135
	v_rcp_f32_e32 v136, v136
	v_rcp_f32_e32 v137, v137
	v_mul_f32_e32 v130, v16, v130
	v_mul_f32_e32 v131, v17, v131
	v_mul_f32_e32 v132, v18, v132
	v_mul_f32_e32 v133, v19, v133
	v_mul_f32_e32 v134, v20, v134
	v_mul_f32_e32 v135, v21, v135
	v_mul_f32_e32 v136, v22, v136
	v_mul_f32_e32 v137, v23, v137
	v_mul_f32_e32 v130, v24, v130
	v_mul_f32_e32 v131, v25, v131
	v_mul_f32_e32 v132, v26, v132
	v_mul_f32_e32 v133, v27, v133
	v_mul_f32_e32 v134, v28, v134
	v_mul_f32_e32 v135, v29, v135
	v_mul_f32_e32 v136, v30, v136
	v_mul_f32_e32 v137, v31, v137
	v_cvt_pk_bf16_f32 v16, v130, v131
	v_cvt_pk_bf16_f32 v17, v132, v133
	v_cvt_pk_bf16_f32 v18, v134, v135
	v_cvt_pk_bf16_f32 v19, v136, v137
	ds_write_b64 v245, v[16:17] offset:1280
	ds_write_b64 v245, v[18:19] offset:1312
	v_mul_f32_e32 v130, 0xbfb8aa3b, v32
	v_mul_f32_e32 v131, 0xbfb8aa3b, v33
	v_mul_f32_e32 v132, 0xbfb8aa3b, v34
	v_mul_f32_e32 v133, 0xbfb8aa3b, v35
	v_mul_f32_e32 v134, 0xbfb8aa3b, v36
	v_mul_f32_e32 v135, 0xbfb8aa3b, v37
	v_mul_f32_e32 v136, 0xbfb8aa3b, v38
	v_mul_f32_e32 v137, 0xbfb8aa3b, v39
	v_exp_f32_e32 v130, v130
	v_exp_f32_e32 v131, v131
	v_exp_f32_e32 v132, v132
	v_exp_f32_e32 v133, v133
	v_exp_f32_e32 v134, v134
	v_exp_f32_e32 v135, v135
	v_exp_f32_e32 v136, v136
	v_exp_f32_e32 v137, v137
	v_add_f32_e32 v130, 1.0, v130
	v_add_f32_e32 v131, 1.0, v131
	v_add_f32_e32 v132, 1.0, v132
	v_add_f32_e32 v133, 1.0, v133
	v_add_f32_e32 v134, 1.0, v134
	v_add_f32_e32 v135, 1.0, v135
	v_add_f32_e32 v136, 1.0, v136
	v_add_f32_e32 v137, 1.0, v137
	v_rcp_f32_e32 v130, v130
	v_rcp_f32_e32 v131, v131
	v_rcp_f32_e32 v132, v132
	v_rcp_f32_e32 v133, v133
	v_rcp_f32_e32 v134, v134
	v_rcp_f32_e32 v135, v135
	v_rcp_f32_e32 v136, v136
	v_rcp_f32_e32 v137, v137
	v_mul_f32_e32 v130, v32, v130
	v_mul_f32_e32 v131, v33, v131
	v_mul_f32_e32 v132, v34, v132
	v_mul_f32_e32 v133, v35, v133
	v_mul_f32_e32 v134, v36, v134
	v_mul_f32_e32 v135, v37, v135
	v_mul_f32_e32 v136, v38, v136
	v_mul_f32_e32 v137, v39, v137
	v_mul_f32_e32 v130, v40, v130
	v_mul_f32_e32 v131, v41, v131
	v_mul_f32_e32 v132, v42, v132
	v_mul_f32_e32 v133, v43, v133
	v_mul_f32_e32 v134, v44, v134
	v_mul_f32_e32 v135, v45, v135
	v_mul_f32_e32 v136, v46, v136
	v_mul_f32_e32 v137, v47, v137
	v_cvt_pk_bf16_f32 v32, v130, v131
	v_cvt_pk_bf16_f32 v33, v132, v133
	v_cvt_pk_bf16_f32 v34, v134, v135
	v_cvt_pk_bf16_f32 v35, v136, v137
	ds_write_b64 v245, v[32:33] offset:2560
	ds_write_b64 v245, v[34:35] offset:2592
	v_mul_f32_e32 v130, 0xbfb8aa3b, v48
	v_mul_f32_e32 v131, 0xbfb8aa3b, v49
	v_mul_f32_e32 v132, 0xbfb8aa3b, v50
	v_mul_f32_e32 v133, 0xbfb8aa3b, v51
	v_mul_f32_e32 v134, 0xbfb8aa3b, v52
	v_mul_f32_e32 v135, 0xbfb8aa3b, v53
	v_mul_f32_e32 v136, 0xbfb8aa3b, v54
	v_mul_f32_e32 v137, 0xbfb8aa3b, v55
	v_exp_f32_e32 v130, v130
	v_exp_f32_e32 v131, v131
	v_exp_f32_e32 v132, v132
	v_exp_f32_e32 v133, v133
	v_exp_f32_e32 v134, v134
	v_exp_f32_e32 v135, v135
	v_exp_f32_e32 v136, v136
	v_exp_f32_e32 v137, v137
	v_add_f32_e32 v130, 1.0, v130
	v_add_f32_e32 v131, 1.0, v131
	v_add_f32_e32 v132, 1.0, v132
	v_add_f32_e32 v133, 1.0, v133
	v_add_f32_e32 v134, 1.0, v134
	v_add_f32_e32 v135, 1.0, v135
	v_add_f32_e32 v136, 1.0, v136
	v_add_f32_e32 v137, 1.0, v137
	v_rcp_f32_e32 v130, v130
	v_rcp_f32_e32 v131, v131
	v_rcp_f32_e32 v132, v132
	v_rcp_f32_e32 v133, v133
	v_rcp_f32_e32 v134, v134
	v_rcp_f32_e32 v135, v135
	v_rcp_f32_e32 v136, v136
	v_rcp_f32_e32 v137, v137
	v_mul_f32_e32 v130, v48, v130
	v_mul_f32_e32 v131, v49, v131
	v_mul_f32_e32 v132, v50, v132
	v_mul_f32_e32 v133, v51, v133
	v_mul_f32_e32 v134, v52, v134
	v_mul_f32_e32 v135, v53, v135
	v_mul_f32_e32 v136, v54, v136
	v_mul_f32_e32 v137, v55, v137
	v_mul_f32_e32 v130, v56, v130
	v_mul_f32_e32 v131, v57, v131
	v_mul_f32_e32 v132, v58, v132
	v_mul_f32_e32 v133, v59, v133
	v_mul_f32_e32 v134, v60, v134
	v_mul_f32_e32 v135, v61, v135
	v_mul_f32_e32 v136, v62, v136
	v_mul_f32_e32 v137, v63, v137
	v_cvt_pk_bf16_f32 v48, v130, v131
	v_cvt_pk_bf16_f32 v49, v132, v133
	v_cvt_pk_bf16_f32 v50, v134, v135
	v_cvt_pk_bf16_f32 v51, v136, v137
	ds_write_b64 v245, v[48:49] offset:3840
	ds_write_b64 v245, v[50:51] offset:3872
	s_waitcnt lgkmcnt(0)
	ds_read_b128 v[138:141], v246 offset:0
	ds_read_b128 v[142:145], v246 offset:1280
	ds_read_b128 v[146:149], v246 offset:2560
	ds_read_b128 v[150:153], v246 offset:3840
	s_mov_b64 s[18:19], s[20:21]
	s_waitcnt lgkmcnt(3)
	global_store_dwordx4 v239, v[138:141], s[18:19]
	s_add_u32 s18, s18, 0x16000
	s_addc_u32 s19, s19, 0
	s_waitcnt lgkmcnt(2)
	global_store_dwordx4 v239, v[142:145], s[18:19]
	s_add_u32 s18, s18, 0x16000
	s_addc_u32 s19, s19, 0
	s_waitcnt lgkmcnt(1)
	global_store_dwordx4 v239, v[146:149], s[18:19]
	s_add_u32 s18, s18, 0x16000
	s_addc_u32 s19, s19, 0
	s_waitcnt lgkmcnt(0)
	global_store_dwordx4 v239, v[150:153], s[18:19]
	s_barrier
	s_add_u32 s15, s15, s16
	s_branch .Lf8_tile
.Lf8_end:
.LBB0_961:
	s_cmp_lt_i32 s61, 9
	s_cbranch_scc1 .LBB0_1015
	s_waitcnt vmcnt(0)
	s_waitcnt vmcnt(63) expcnt(7) lgkmcnt(15)
	s_barrier
	s_and_saveexec_b64 s[4:5], s[52:53]
	s_cbranch_execz .LBB0_1014
	v_mov_b32_e32 v0, 0x12000
	s_waitcnt vmcnt(0) expcnt(0) lgkmcnt(0)
	ds_read_b32 v2, v0
	v_mov_b32_e32 v0, 0x12004
	ds_read_b32 v0, v0
	s_waitcnt lgkmcnt(1)
	v_cmp_ne_u32_e32 vcc, 0, v2
	s_cbranch_vccnz .LBB0_978
	s_load_dwordx2 s[2:3], s[0:1], 0xf0
	s_load_dword s9, s[0:1], 0xf8
	s_add_u32 s6, s56, 0x1457a300
	s_addc_u32 s7, s57, 0
	s_add_u32 s8, s56, 0x1457a500
	s_waitcnt lgkmcnt(0)
	s_mul_i32 s2, s3, s2
	s_mul_i32 s2, s2, s9
	s_addc_u32 s9, s57, 0
	s_add_u32 s10, s56, 0x1457a600
	s_addc_u32 s11, s57, 0
	s_add_u32 s12, s56, 0x1457a700
	s_addc_u32 s13, s57, 0
	s_add_u32 s14, s56, 0x1457a800
	s_addc_u32 s15, s57, 0
	s_add_u32 s16, s56, 0x1457a900
	s_addc_u32 s17, s57, 0
	s_add_u32 s18, s56, 0x1457aa00
	s_addc_u32 s19, s57, 0
	s_add_u32 s20, s56, 0x1457ab00
	s_addc_u32 s21, s57, 0
	s_add_u32 s22, s56, 0x1457ac00
	s_addc_u32 s23, s57, 0
	s_add_u32 s24, s56, 0x1457ad00
	s_addc_u32 s25, s57, 0
	s_add_u32 s26, s56, 0x1457ae00
	s_addc_u32 s27, s57, 0
	s_add_u32 s28, s56, 0x1457af00
	s_addc_u32 s29, s57, 0
	s_add_u32 s30, s56, 0x1457b000
	s_addc_u32 s31, s57, 0
	s_add_u32 s34, s56, 0x1457b100
	s_addc_u32 s35, s57, 0
	s_add_u32 s36, s56, 0x1457b200
	s_addc_u32 s37, s57, 0
	s_add_u32 s38, s56, 0x1457b300
	s_addc_u32 s39, s57, 0
	s_add_u32 s40, s56, 0x1457b400
	s_addc_u32 s41, s57, 0
	s_mov_b32 s3, 1
	v_mov_b32_e32 v16, 0
	s_branch .LBB0_966

.LBB0_1386:
	s_cmp_gt_i32 s60, 15
	s_cselect_b64 s[2:3], -1, 0
	s_cmp_lt_i32 s61, 15
	s_cselect_b64 s[4:5], -1, 0
	s_or_b64 s[2:3], s[2:3], s[4:5]
	s_and_b64 vcc, exec, s[2:3]
	s_cbranch_vccnz .LBB0_1450
	s_load_dwordx2 s[4:5], s[0:1], 0xe0
	s_load_dword s16, s[0:1], 0xf0
	v_and_b32_e32 v240, 63, v162
	v_lshrrev_b32_e32 v247, 6, v162
	v_lshrrev_b32_e32 v242, 3, v240
	v_lshl_add_u32 v242, v247, 5, v242
	v_and_b32_e32 v243, 7, v240
	v_lshrrev_b32_e32 v244, 4, v240
	v_xor_b32_e32 v243, v243, v244
	v_lshlrev_b32_e32 v243, 4, v243
	v_mov_b32_e32 v241, 0x800
	v_mad_u32_u24 v248, v242, v241, v243
	v_xor_b32_e32 v249, 64, v248
	v_add_u32_e32 v249, 0x4000, v249
	v_add_u32_e32 v250, 0x8000, v248
	v_xor_b32_e32 v251, 64, v248
	v_add_u32_e32 v251, 0xc000, v251
	v_and_b32_e32 v241, 15, v240
	v_lshrrev_b32_e32 v242, 1, v241
	v_xor_b32_e32 v242, v242, v244
	v_lshlrev_b32_e32 v242, 4, v242
	v_lshl_or_b32 v242, v241, 7, v242
	v_lshrrev_b32_e32 v243, 1, v247
	v_lshl_or_b32 v252, v243, 13, v242
	v_xor_b32_e32 v253, 64, v252
	v_and_b32_e32 v243, 1, v247
	v_lshl_or_b32 v254, v243, 13, v242
	v_xor_b32_e32 v255, 64, v254
	v_and_b32_e32 v240, 63, v162
	v_and_b32_e32 v241, 15, v240
	v_lshrrev_b32_e32 v242, 4, v240
	v_mul_u32_u24_e32 v245, 0x1400, v247
	v_mul_u32_u24_e32 v243, 80, v241
	v_add_u32_e32 v243, v243, v245
	v_lshl_add_u32 v244, v242, 3, v243
	v_lshrrev_b32_e32 v243, 2, v240
	v_mul_u32_u24_e32 v246, 80, v243
	v_add_u32_e32 v246, v246, v245
	v_and_b32_e32 v241, 3, v240
	v_lshl_add_u32 v246, v241, 4, v246
	v_mov_b32_e32 v245, v244
	v_lshrrev_b32_e32 v242, 1, v247
	v_lshl_add_u32 v243, v242, 6, v243
	v_mov_b32_e32 v242, 0x1600
	v_mul_u32_u24_e32 v243, v243, v242
	v_and_b32_e32 v242, 1, v247
	v_lshl_add_u32 v243, v242, 6, v243
	v_lshl_add_u32 v239, v241, 4, v243
	s_waitcnt lgkmcnt(0)
	s_add_u32 s26, s4, 0x8b7a100
	s_addc_u32 s27, s5, 0
	s_add_u32 s28, s4, 0x2f80000
	s_addc_u32 s29, s5, 0
	s_mov_b32 s15, s58

.Lf15_end:
.LBB0_1396:
	s_cmp_lt_i32 s61, 16
	s_cbranch_scc1 .LBB0_1450
	s_waitcnt vmcnt(0)
	s_waitcnt vmcnt(63) expcnt(7) lgkmcnt(15)
	s_barrier
	s_and_saveexec_b64 s[4:5], s[52:53]
	s_cbranch_execz .LBB0_1449
	v_mov_b32_e32 v0, 0x12000
	s_waitcnt vmcnt(0) expcnt(0) lgkmcnt(0)
	ds_read_b32 v2, v0
	v_mov_b32_e32 v0, 0x12004
	ds_read_b32 v0, v0
	s_waitcnt lgkmcnt(1)
	v_cmp_ne_u32_e32 vcc, 0, v2
	s_cbranch_vccnz .LBB0_1413
	s_load_dwordx2 s[2:3], s[0:1], 0xf0
	s_load_dword s9, s[0:1], 0xf8
	s_add_u32 s6, s56, 0x1457a300
	s_addc_u32 s7, s57, 0
	s_add_u32 s8, s56, 0x1457a500
	s_waitcnt lgkmcnt(0)
	s_mul_i32 s2, s3, s2
	s_mul_i32 s2, s2, s9
	s_addc_u32 s9, s57, 0
	s_add_u32 s10, s56, 0x1457a600
	s_addc_u32 s11, s57, 0
	s_add_u32 s12, s56, 0x1457a700
	s_addc_u32 s13, s57, 0
	s_add_u32 s14, s56, 0x1457a800
	s_addc_u32 s15, s57, 0
	s_add_u32 s16, s56, 0x1457a900
	s_addc_u32 s17, s57, 0
	s_add_u32 s18, s56, 0x1457aa00
	s_addc_u32 s19, s57, 0
	s_add_u32 s20, s56, 0x1457ab00
	s_addc_u32 s21, s57, 0
	s_add_u32 s22, s56, 0x1457ac00
	s_addc_u32 s23, s57, 0
	s_add_u32 s24, s56, 0x1457ad00
	s_addc_u32 s25, s57, 0
	s_add_u32 s26, s56, 0x1457ae00
	s_addc_u32 s27, s57, 0
	s_add_u32 s28, s56, 0x1457af00
	s_addc_u32 s29, s57, 0
	s_add_u32 s30, s56, 0x1457b000
	s_addc_u32 s31, s57, 0
	s_add_u32 s34, s56, 0x1457b100
	s_addc_u32 s35, s57, 0
	s_add_u32 s36, s56, 0x1457b200
	s_addc_u32 s37, s57, 0
	s_add_u32 s38, s56, 0x1457b300
	s_addc_u32 s39, s57, 0
	s_add_u32 s40, s56, 0x1457b400
	s_addc_u32 s41, s57, 0
	s_mov_b32 s3, 1
	v_mov_b32_e32 v16, 0
	s_branch .LBB0_1401

.LBB0_2410:
	s_cmp_gt_i32 s60, 24
	s_cselect_b64 s[2:3], -1, 0
	s_cmp_lt_i32 s61, 24
	s_cselect_b64 s[4:5], -1, 0
	s_or_b64 s[2:3], s[2:3], s[4:5]
	s_and_b64 vcc, exec, s[2:3]
	s_cbranch_vccnz .LBB0_2474
	s_load_dwordx2 s[4:5], s[0:1], 0xe0
	s_load_dword s16, s[0:1], 0xf0
	v_and_b32_e32 v240, 63, v162
	v_lshrrev_b32_e32 v247, 6, v162
	v_lshrrev_b32_e32 v242, 3, v240
	v_lshl_add_u32 v242, v247, 5, v242
	v_and_b32_e32 v243, 7, v240
	v_lshrrev_b32_e32 v244, 4, v240
	v_xor_b32_e32 v243, v243, v244
	v_lshlrev_b32_e32 v243, 4, v243
	v_mov_b32_e32 v241, 0x800
	v_mad_u32_u24 v248, v242, v241, v243
	v_xor_b32_e32 v249, 64, v248
	v_add_u32_e32 v249, 0x4000, v249
	v_add_u32_e32 v250, 0x8000, v248
	v_xor_b32_e32 v251, 64, v248
	v_add_u32_e32 v251, 0xc000, v251
	v_and_b32_e32 v241, 15, v240
	v_lshrrev_b32_e32 v242, 1, v241
	v_xor_b32_e32 v242, v242, v244
	v_lshlrev_b32_e32 v242, 4, v242
	v_lshl_or_b32 v242, v241, 7, v242
	v_lshrrev_b32_e32 v243, 1, v247
	v_lshl_or_b32 v252, v243, 13, v242
	v_xor_b32_e32 v253, 64, v252
	v_and_b32_e32 v243, 1, v247
	v_lshl_or_b32 v254, v243, 13, v242
	v_xor_b32_e32 v255, 64, v254
	v_and_b32_e32 v240, 63, v162
	v_and_b32_e32 v241, 15, v240
	v_lshrrev_b32_e32 v242, 4, v240
	v_mul_u32_u24_e32 v245, 0x1400, v247
	v_mul_u32_u24_e32 v243, 80, v241
	v_add_u32_e32 v243, v243, v245
	v_lshl_add_u32 v244, v242, 3, v243
	v_lshrrev_b32_e32 v243, 2, v240
	v_mul_u32_u24_e32 v246, 80, v243
	v_add_u32_e32 v246, v246, v245
	v_and_b32_e32 v241, 3, v240
	v_lshl_add_u32 v246, v241, 4, v246
	v_mov_b32_e32 v245, v244
	v_lshrrev_b32_e32 v242, 1, v247
	v_lshl_add_u32 v243, v242, 6, v243
	v_mov_b32_e32 v242, 0x1600
	v_mul_u32_u24_e32 v243, v243, v242
	v_and_b32_e32 v242, 1, v247
	v_lshl_add_u32 v243, v242, 6, v243
	v_lshl_add_u32 v239, v241, 4, v243
	s_waitcnt lgkmcnt(0)
	s_add_u32 s26, s4, 0x8b7a100
	s_addc_u32 s27, s5, 0
	s_add_u32 s28, s4, 0x3a80000
	s_addc_u32 s29, s5, 0
	s_mov_b32 s15, s58

.Lf24_end:
.LBB0_2420:
	s_cmp_lt_i32 s61, 25
	s_cbranch_scc1 .LBB0_2474
	s_waitcnt vmcnt(0)
	s_waitcnt vmcnt(63) expcnt(7) lgkmcnt(15)
	s_barrier
	s_and_saveexec_b64 s[4:5], s[52:53]
	s_cbranch_execz .LBB0_2473
	v_mov_b32_e32 v0, 0x12000
	s_waitcnt vmcnt(0) expcnt(0) lgkmcnt(0)
	ds_read_b32 v2, v0
	v_mov_b32_e32 v0, 0x12004
	ds_read_b32 v0, v0
	s_waitcnt lgkmcnt(1)
	v_cmp_ne_u32_e32 vcc, 0, v2
	s_cbranch_vccnz .LBB0_2437
	s_load_dwordx2 s[2:3], s[0:1], 0xf0
	s_load_dword s9, s[0:1], 0xf8
	s_add_u32 s6, s56, 0x1457a300
	s_addc_u32 s7, s57, 0
	s_add_u32 s8, s56, 0x1457a500
	s_waitcnt lgkmcnt(0)
	s_mul_i32 s2, s3, s2
	s_mul_i32 s2, s2, s9
	s_addc_u32 s9, s57, 0
	s_add_u32 s10, s56, 0x1457a600
	s_addc_u32 s11, s57, 0
	s_add_u32 s12, s56, 0x1457a700
	s_addc_u32 s13, s57, 0
	s_add_u32 s14, s56, 0x1457a800
	s_addc_u32 s15, s57, 0
	s_add_u32 s16, s56, 0x1457a900
	s_addc_u32 s17, s57, 0
	s_add_u32 s18, s56, 0x1457aa00
	s_addc_u32 s19, s57, 0
	s_add_u32 s20, s56, 0x1457ab00
	s_addc_u32 s21, s57, 0
	s_add_u32 s22, s56, 0x1457ac00
	s_addc_u32 s23, s57, 0
	s_add_u32 s24, s56, 0x1457ad00
	s_addc_u32 s25, s57, 0
	s_add_u32 s26, s56, 0x1457ae00
	s_addc_u32 s27, s57, 0
	s_add_u32 s28, s56, 0x1457af00
	s_addc_u32 s29, s57, 0
	s_add_u32 s30, s56, 0x1457b000
	s_addc_u32 s31, s57, 0
	s_add_u32 s34, s56, 0x1457b100
	s_addc_u32 s35, s57, 0
	s_add_u32 s36, s56, 0x1457b200
	s_addc_u32 s37, s57, 0
	s_add_u32 s38, s56, 0x1457b300
	s_addc_u32 s39, s57, 0
	s_add_u32 s40, s56, 0x1457b400
	s_addc_u32 s41, s57, 0
	s_mov_b32 s3, 1
	v_mov_b32_e32 v16, 0
	s_branch .LBB0_2425

.LBB0_2845:
	s_cmp_gt_i32 s60, 31
	s_cselect_b64 s[2:3], -1, 0
	s_cmp_lt_i32 s61, 31
	s_cselect_b64 s[4:5], -1, 0
	s_or_b64 s[2:3], s[2:3], s[4:5]
	s_and_b64 vcc, exec, s[2:3]
	s_cbranch_vccnz .LBB0_2909
	s_load_dwordx2 s[4:5], s[0:1], 0xe0
	s_load_dword s16, s[0:1], 0xf0
	v_and_b32_e32 v240, 63, v162
	v_lshrrev_b32_e32 v247, 6, v162
	v_lshrrev_b32_e32 v242, 3, v240
	v_lshl_add_u32 v242, v247, 5, v242
	v_and_b32_e32 v243, 7, v240
	v_lshrrev_b32_e32 v244, 4, v240
	v_xor_b32_e32 v243, v243, v244
	v_lshlrev_b32_e32 v243, 4, v243
	v_mov_b32_e32 v241, 0x800
	v_mad_u32_u24 v248, v242, v241, v243
	v_xor_b32_e32 v249, 64, v248
	v_add_u32_e32 v249, 0x4000, v249
	v_add_u32_e32 v250, 0x8000, v248
	v_xor_b32_e32 v251, 64, v248
	v_add_u32_e32 v251, 0xc000, v251
	v_and_b32_e32 v241, 15, v240
	v_lshrrev_b32_e32 v242, 1, v241
	v_xor_b32_e32 v242, v242, v244
	v_lshlrev_b32_e32 v242, 4, v242
	v_lshl_or_b32 v242, v241, 7, v242
	v_lshrrev_b32_e32 v243, 1, v247
	v_lshl_or_b32 v252, v243, 13, v242
	v_xor_b32_e32 v253, 64, v252
	v_and_b32_e32 v243, 1, v247
	v_lshl_or_b32 v254, v243, 13, v242
	v_xor_b32_e32 v255, 64, v254
	v_and_b32_e32 v240, 63, v162
	v_and_b32_e32 v241, 15, v240
	v_lshrrev_b32_e32 v242, 4, v240
	v_mul_u32_u24_e32 v245, 0x1400, v247
	v_mul_u32_u24_e32 v243, 80, v241
	v_add_u32_e32 v243, v243, v245
	v_lshl_add_u32 v244, v242, 3, v243
	v_lshrrev_b32_e32 v243, 2, v240
	v_mul_u32_u24_e32 v246, 80, v243
	v_add_u32_e32 v246, v246, v245
	v_and_b32_e32 v241, 3, v240
	v_lshl_add_u32 v246, v241, 4, v246
	v_mov_b32_e32 v245, v244
	v_lshrrev_b32_e32 v242, 1, v247
	v_lshl_add_u32 v243, v242, 6, v243
	v_mov_b32_e32 v242, 0x1600
	v_mul_u32_u24_e32 v243, v243, v242
	v_and_b32_e32 v242, 1, v247
	v_lshl_add_u32 v243, v242, 6, v243
	v_lshl_add_u32 v239, v241, 4, v243
	s_waitcnt lgkmcnt(0)
	s_add_u32 s26, s4, 0x8b7a100
	s_addc_u32 s27, s5, 0
	s_add_u32 s28, s4, 0x4580000
	s_addc_u32 s29, s5, 0
	s_mov_b32 s15, s58

.Lf31_end:
.LBB0_2855:
	s_cmp_lt_i32 s61, 32
	s_cbranch_scc1 .LBB0_2909
	s_waitcnt vmcnt(0)
	s_waitcnt vmcnt(63) expcnt(7) lgkmcnt(15)
	s_barrier
	s_and_saveexec_b64 s[4:5], s[52:53]
	s_cbranch_execz .LBB0_2908
	v_mov_b32_e32 v0, 0x12000
	s_waitcnt vmcnt(0) expcnt(0) lgkmcnt(0)
	ds_read_b32 v2, v0
	v_mov_b32_e32 v0, 0x12004
	ds_read_b32 v0, v0
	s_waitcnt lgkmcnt(1)
	v_cmp_ne_u32_e32 vcc, 0, v2
	s_cbranch_vccnz .LBB0_2872
	s_load_dwordx2 s[2:3], s[0:1], 0xf0
	s_load_dword s9, s[0:1], 0xf8
	s_add_u32 s6, s56, 0x1457a300
	s_addc_u32 s7, s57, 0
	s_add_u32 s8, s56, 0x1457a500
	s_waitcnt lgkmcnt(0)
	s_mul_i32 s2, s3, s2
	s_mul_i32 s2, s2, s9
	s_addc_u32 s9, s57, 0
	s_add_u32 s10, s56, 0x1457a600
	s_addc_u32 s11, s57, 0
	s_add_u32 s12, s56, 0x1457a700
	s_addc_u32 s13, s57, 0
	s_add_u32 s14, s56, 0x1457a800
	s_addc_u32 s15, s57, 0
	s_add_u32 s16, s56, 0x1457a900
	s_addc_u32 s17, s57, 0
	s_add_u32 s18, s56, 0x1457aa00
	s_addc_u32 s19, s57, 0
	s_add_u32 s20, s56, 0x1457ab00
	s_addc_u32 s21, s57, 0
	s_add_u32 s22, s56, 0x1457ac00
	s_addc_u32 s23, s57, 0
	s_add_u32 s24, s56, 0x1457ad00
	s_addc_u32 s25, s57, 0
	s_add_u32 s26, s56, 0x1457ae00
	s_addc_u32 s27, s57, 0
	s_add_u32 s28, s56, 0x1457af00
	s_addc_u32 s29, s57, 0
	s_add_u32 s30, s56, 0x1457b000
	s_addc_u32 s31, s57, 0
	s_add_u32 s34, s56, 0x1457b100
	s_addc_u32 s35, s57, 0
	s_add_u32 s36, s56, 0x1457b200
	s_addc_u32 s37, s57, 0
	s_add_u32 s38, s56, 0x1457b300
	s_addc_u32 s39, s57, 0
	s_add_u32 s40, s56, 0x1457b400
	s_addc_u32 s41, s57, 0
	s_mov_b32 s3, 1
	v_mov_b32_e32 v16, 0
	s_branch .LBB0_2860
